# attention fast trip: step-closing wait+barrier moved up one P.V MFMA gap (tail MFMA + 4 exps run after the barrier)
# speedup vs baseline: 1.0089x; 1.0089x over previous
.Lf3_0_486:
	s_waitcnt lgkmcnt(14)
	v_mfma_f32_32x32x16_bf16 v[18:33], v[138:141], v[178:181], v[18:33]
	v_exp_f32_e32 v98, v98
	v_exp_f32_e32 v99, v99
	v_exp_f32_e32 v100, v100
	v_exp_f32_e32 v101, v101
	s_waitcnt lgkmcnt(12)
	v_mfma_f32_32x32x16_bf16 v[2:17], v[138:141], v[174:177], v[2:17]
	v_exp_f32_e32 v102, v102
	v_exp_f32_e32 v103, v103
	v_exp_f32_e32 v104, v104
	v_exp_f32_e32 v105, v105
	ds_read_b128 v[62:65], v202 offset:16384
	ds_read_b128 v[174:177], v202 offset:16896
	s_waitcnt lgkmcnt(12)
	v_mfma_f32_32x32x16_bf16 v[18:33], v[130:133], v[66:69], v[18:33]
	v_exp_f32_e32 v106, v106
	v_exp_f32_e32 v107, v107
	v_exp_f32_e32 v108, v108
	v_exp_f32_e32 v109, v109
	ds_read_b128 v[178:181], v202 offset:18432
	ds_read_b128 v[170:173], v202 offset:18944
	s_waitcnt lgkmcnt(12)
	v_mfma_f32_32x32x16_bf16 v[2:17], v[130:133], v[70:73], v[2:17]
	v_exp_f32_e32 v110, v110
	v_exp_f32_e32 v111, v111
	v_exp_f32_e32 v112, v112
	v_exp_f32_e32 v113, v113
	ds_read_b128 v[166:169], v202 offset:20480
	ds_read_b128 v[162:165], v202 offset:20992
	s_waitcnt lgkmcnt(12)
	v_mfma_f32_32x32x16_bf16 v[18:33], v[122:125], v[74:77], v[18:33]
	v_exp_f32_e32 v82, v82
	v_exp_f32_e32 v83, v83
	v_exp_f32_e32 v84, v84
	v_exp_f32_e32 v85, v85
	ds_read_b128 v[158:161], v202 offset:22528
	ds_read_b128 v[154:157], v202 offset:23040
	s_waitcnt lgkmcnt(12)
	v_mfma_f32_32x32x16_bf16 v[2:17], v[122:125], v[50:53], v[2:17]
	v_exp_f32_e32 v86, v86
	v_exp_f32_e32 v87, v87
	v_exp_f32_e32 v88, v88
	v_exp_f32_e32 v89, v89
	s_waitcnt lgkmcnt(10)
	v_mfma_f32_32x32x16_bf16 v[18:33], v[114:117], v[54:57], v[18:33]
	v_exp_f32_e32 v90, v90
	v_exp_f32_e32 v91, v91
	v_exp_f32_e32 v92, v92
	v_exp_f32_e32 v93, v93
	s_waitcnt vmcnt(2) lgkmcnt(0)
	s_barrier
	s_waitcnt lgkmcnt(8)
	v_mfma_f32_32x32x16_bf16 v[2:17], v[114:117], v[58:61], v[2:17]
	v_exp_f32_e32 v94, v94
	v_exp_f32_e32 v95, v95
	v_exp_f32_e32 v96, v96
	v_exp_f32_e32 v97, v97

.Lf3_0_489:
	s_waitcnt lgkmcnt(14)
	v_mfma_f32_32x32x16_bf16 v[18:33], v[138:141], v[150:153], v[18:33]
	v_exp_f32_e32 v66, v66
	v_exp_f32_e32 v67, v67
	v_exp_f32_e32 v68, v68
	v_exp_f32_e32 v69, v69
	s_waitcnt lgkmcnt(12)
	v_mfma_f32_32x32x16_bf16 v[2:17], v[138:141], v[146:149], v[2:17]
	v_exp_f32_e32 v70, v70
	v_exp_f32_e32 v71, v71
	v_exp_f32_e32 v72, v72
	v_exp_f32_e32 v73, v73
	ds_read_b128 v[174:177], v202 offset:0
	ds_read_b128 v[170:173], v202 offset:512
	s_waitcnt lgkmcnt(12)
	v_mfma_f32_32x32x16_bf16 v[18:33], v[130:133], v[98:101], v[18:33]
	v_exp_f32_e32 v74, v74
	v_exp_f32_e32 v75, v75
	v_exp_f32_e32 v76, v76
	v_exp_f32_e32 v77, v77
	ds_read_b128 v[166:169], v202 offset:2048
	ds_read_b128 v[162:165], v202 offset:2560
	s_waitcnt lgkmcnt(12)
	v_mfma_f32_32x32x16_bf16 v[2:17], v[130:133], v[102:105], v[2:17]
	v_exp_f32_e32 v78, v78
	v_exp_f32_e32 v79, v79
	v_exp_f32_e32 v80, v80
	v_exp_f32_e32 v81, v81
	ds_read_b128 v[158:161], v202 offset:4096
	ds_read_b128 v[154:157], v202 offset:4608
	s_waitcnt lgkmcnt(12)
	v_mfma_f32_32x32x16_bf16 v[18:33], v[122:125], v[106:109], v[18:33]
	v_exp_f32_e32 v50, v50
	v_exp_f32_e32 v51, v51
	v_exp_f32_e32 v52, v52
	v_exp_f32_e32 v53, v53
	ds_read_b128 v[150:153], v202 offset:6144
	ds_read_b128 v[146:149], v202 offset:6656
	s_waitcnt lgkmcnt(12)
	v_mfma_f32_32x32x16_bf16 v[2:17], v[122:125], v[82:85], v[2:17]
	v_exp_f32_e32 v54, v54
	v_exp_f32_e32 v55, v55
	v_exp_f32_e32 v56, v56
	v_exp_f32_e32 v57, v57
	s_waitcnt lgkmcnt(10)
	v_mfma_f32_32x32x16_bf16 v[18:33], v[114:117], v[86:89], v[18:33]
	v_exp_f32_e32 v58, v58
	v_exp_f32_e32 v59, v59
	v_exp_f32_e32 v60, v60
	v_exp_f32_e32 v61, v61
	s_waitcnt vmcnt(2) lgkmcnt(0)
	s_barrier
	s_waitcnt lgkmcnt(8)
	v_mfma_f32_32x32x16_bf16 v[2:17], v[114:117], v[90:93], v[2:17]
	v_exp_f32_e32 v62, v62
	v_exp_f32_e32 v63, v63
	v_exp_f32_e32 v64, v64
	v_exp_f32_e32 v65, v65

.Lf3_1_486:
	s_waitcnt lgkmcnt(14)
	v_mfma_f32_32x32x16_bf16 v[18:33], v[138:141], v[178:181], v[18:33]
	v_exp_f32_e32 v98, v98
	v_exp_f32_e32 v99, v99
	v_exp_f32_e32 v100, v100
	v_exp_f32_e32 v101, v101
	s_waitcnt lgkmcnt(12)
	v_mfma_f32_32x32x16_bf16 v[2:17], v[138:141], v[174:177], v[2:17]
	v_exp_f32_e32 v102, v102
	v_exp_f32_e32 v103, v103
	v_exp_f32_e32 v104, v104
	v_exp_f32_e32 v105, v105
	ds_read_b128 v[62:65], v202 offset:8192
	ds_read_b128 v[174:177], v202 offset:8704
	s_waitcnt lgkmcnt(12)
	v_mfma_f32_32x32x16_bf16 v[18:33], v[130:133], v[66:69], v[18:33]
	v_exp_f32_e32 v106, v106
	v_exp_f32_e32 v107, v107
	v_exp_f32_e32 v108, v108
	v_exp_f32_e32 v109, v109
	ds_read_b128 v[178:181], v202 offset:10240
	ds_read_b128 v[170:173], v202 offset:10752
	s_waitcnt lgkmcnt(12)
	v_mfma_f32_32x32x16_bf16 v[2:17], v[130:133], v[70:73], v[2:17]
	v_exp_f32_e32 v110, v110
	v_exp_f32_e32 v111, v111
	v_exp_f32_e32 v112, v112
	v_exp_f32_e32 v113, v113
	ds_read_b128 v[166:169], v202 offset:12288
	ds_read_b128 v[162:165], v202 offset:12800
	s_waitcnt lgkmcnt(12)
	v_mfma_f32_32x32x16_bf16 v[18:33], v[122:125], v[74:77], v[18:33]
	v_exp_f32_e32 v82, v82
	v_exp_f32_e32 v83, v83
	v_exp_f32_e32 v84, v84
	v_exp_f32_e32 v85, v85
	ds_read_b128 v[158:161], v202 offset:14336
	ds_read_b128 v[154:157], v202 offset:14848
	s_waitcnt lgkmcnt(12)
	v_mfma_f32_32x32x16_bf16 v[2:17], v[122:125], v[50:53], v[2:17]
	v_exp_f32_e32 v86, v86
	v_exp_f32_e32 v87, v87
	v_exp_f32_e32 v88, v88
	v_exp_f32_e32 v89, v89
	s_waitcnt lgkmcnt(10)
	v_mfma_f32_32x32x16_bf16 v[18:33], v[114:117], v[54:57], v[18:33]
	v_exp_f32_e32 v90, v90
	v_exp_f32_e32 v91, v91
	v_exp_f32_e32 v92, v92
	v_exp_f32_e32 v93, v93
	s_waitcnt vmcnt(2) lgkmcnt(0)
	s_barrier
	s_waitcnt lgkmcnt(8)
	v_mfma_f32_32x32x16_bf16 v[2:17], v[114:117], v[58:61], v[2:17]
	v_exp_f32_e32 v94, v94
	v_exp_f32_e32 v95, v95
	v_exp_f32_e32 v96, v96
	v_exp_f32_e32 v97, v97

.Lf3_1_489:
	s_waitcnt lgkmcnt(14)
	v_mfma_f32_32x32x16_bf16 v[18:33], v[138:141], v[150:153], v[18:33]
	v_exp_f32_e32 v66, v66
	v_exp_f32_e32 v67, v67
	v_exp_f32_e32 v68, v68
	v_exp_f32_e32 v69, v69
	s_waitcnt lgkmcnt(12)
	v_mfma_f32_32x32x16_bf16 v[2:17], v[138:141], v[146:149], v[2:17]
	v_exp_f32_e32 v70, v70
	v_exp_f32_e32 v71, v71
	v_exp_f32_e32 v72, v72
	v_exp_f32_e32 v73, v73
	ds_read_b128 v[174:177], v202 offset:16384
	ds_read_b128 v[170:173], v202 offset:16896
	s_waitcnt lgkmcnt(12)
	v_mfma_f32_32x32x16_bf16 v[18:33], v[130:133], v[98:101], v[18:33]
	v_exp_f32_e32 v74, v74
	v_exp_f32_e32 v75, v75
	v_exp_f32_e32 v76, v76
	v_exp_f32_e32 v77, v77
	ds_read_b128 v[166:169], v202 offset:18432
	ds_read_b128 v[162:165], v202 offset:18944
	s_waitcnt lgkmcnt(12)
	v_mfma_f32_32x32x16_bf16 v[2:17], v[130:133], v[102:105], v[2:17]
	v_exp_f32_e32 v78, v78
	v_exp_f32_e32 v79, v79
	v_exp_f32_e32 v80, v80
	v_exp_f32_e32 v81, v81
	ds_read_b128 v[158:161], v202 offset:20480
	ds_read_b128 v[154:157], v202 offset:20992
	s_waitcnt lgkmcnt(12)
	v_mfma_f32_32x32x16_bf16 v[18:33], v[122:125], v[106:109], v[18:33]
	v_exp_f32_e32 v50, v50
	v_exp_f32_e32 v51, v51
	v_exp_f32_e32 v52, v52
	v_exp_f32_e32 v53, v53
	ds_read_b128 v[150:153], v202 offset:22528
	ds_read_b128 v[146:149], v202 offset:23040
	s_waitcnt lgkmcnt(12)
	v_mfma_f32_32x32x16_bf16 v[2:17], v[122:125], v[82:85], v[2:17]
	v_exp_f32_e32 v54, v54
	v_exp_f32_e32 v55, v55
	v_exp_f32_e32 v56, v56
	v_exp_f32_e32 v57, v57
	s_waitcnt lgkmcnt(10)
	v_mfma_f32_32x32x16_bf16 v[18:33], v[114:117], v[86:89], v[18:33]
	v_exp_f32_e32 v58, v58
	v_exp_f32_e32 v59, v59
	v_exp_f32_e32 v60, v60
	v_exp_f32_e32 v61, v61
	s_waitcnt vmcnt(2) lgkmcnt(0)
	s_barrier
	s_waitcnt lgkmcnt(8)
	v_mfma_f32_32x32x16_bf16 v[2:17], v[114:117], v[90:93], v[2:17]
	v_exp_f32_e32 v62, v62
	v_exp_f32_e32 v63, v63
	v_exp_f32_e32 v64, v64
	v_exp_f32_e32 v65, v65

.Lf3_2_486:
	s_waitcnt lgkmcnt(14)
	v_mfma_f32_32x32x16_bf16 v[18:33], v[138:141], v[178:181], v[18:33]
	v_exp_f32_e32 v98, v98
	v_exp_f32_e32 v99, v99
	v_exp_f32_e32 v100, v100
	v_exp_f32_e32 v101, v101
	s_waitcnt lgkmcnt(12)
	v_mfma_f32_32x32x16_bf16 v[2:17], v[138:141], v[174:177], v[2:17]
	v_exp_f32_e32 v102, v102
	v_exp_f32_e32 v103, v103
	v_exp_f32_e32 v104, v104
	v_exp_f32_e32 v105, v105
	ds_read_b128 v[62:65], v202 offset:0
	ds_read_b128 v[174:177], v202 offset:512
	s_waitcnt lgkmcnt(12)
	v_mfma_f32_32x32x16_bf16 v[18:33], v[130:133], v[66:69], v[18:33]
	v_exp_f32_e32 v106, v106
	v_exp_f32_e32 v107, v107
	v_exp_f32_e32 v108, v108
	v_exp_f32_e32 v109, v109
	ds_read_b128 v[178:181], v202 offset:2048
	ds_read_b128 v[170:173], v202 offset:2560
	s_waitcnt lgkmcnt(12)
	v_mfma_f32_32x32x16_bf16 v[2:17], v[130:133], v[70:73], v[2:17]
	v_exp_f32_e32 v110, v110
	v_exp_f32_e32 v111, v111
	v_exp_f32_e32 v112, v112
	v_exp_f32_e32 v113, v113
	ds_read_b128 v[166:169], v202 offset:4096
	ds_read_b128 v[162:165], v202 offset:4608
	s_waitcnt lgkmcnt(12)
	v_mfma_f32_32x32x16_bf16 v[18:33], v[122:125], v[74:77], v[18:33]
	v_exp_f32_e32 v82, v82
	v_exp_f32_e32 v83, v83
	v_exp_f32_e32 v84, v84
	v_exp_f32_e32 v85, v85
	ds_read_b128 v[158:161], v202 offset:6144
	ds_read_b128 v[154:157], v202 offset:6656
	s_waitcnt lgkmcnt(12)
	v_mfma_f32_32x32x16_bf16 v[2:17], v[122:125], v[50:53], v[2:17]
	v_exp_f32_e32 v86, v86
	v_exp_f32_e32 v87, v87
	v_exp_f32_e32 v88, v88
	v_exp_f32_e32 v89, v89
	s_waitcnt lgkmcnt(10)
	v_mfma_f32_32x32x16_bf16 v[18:33], v[114:117], v[54:57], v[18:33]
	v_exp_f32_e32 v90, v90
	v_exp_f32_e32 v91, v91
	v_exp_f32_e32 v92, v92
	v_exp_f32_e32 v93, v93
	s_waitcnt vmcnt(2) lgkmcnt(0)
	s_barrier
	s_waitcnt lgkmcnt(8)
	v_mfma_f32_32x32x16_bf16 v[2:17], v[114:117], v[58:61], v[2:17]
	v_exp_f32_e32 v94, v94
	v_exp_f32_e32 v95, v95
	v_exp_f32_e32 v96, v96
	v_exp_f32_e32 v97, v97

.Lf3_2_489:
	s_waitcnt lgkmcnt(14)
	v_mfma_f32_32x32x16_bf16 v[18:33], v[138:141], v[150:153], v[18:33]
	v_exp_f32_e32 v66, v66
	v_exp_f32_e32 v67, v67
	v_exp_f32_e32 v68, v68
	v_exp_f32_e32 v69, v69
	s_waitcnt lgkmcnt(12)
	v_mfma_f32_32x32x16_bf16 v[2:17], v[138:141], v[146:149], v[2:17]
	v_exp_f32_e32 v70, v70
	v_exp_f32_e32 v71, v71
	v_exp_f32_e32 v72, v72
	v_exp_f32_e32 v73, v73
	ds_read_b128 v[174:177], v202 offset:8192
	ds_read_b128 v[170:173], v202 offset:8704
	s_waitcnt lgkmcnt(12)
	v_mfma_f32_32x32x16_bf16 v[18:33], v[130:133], v[98:101], v[18:33]
	v_exp_f32_e32 v74, v74
	v_exp_f32_e32 v75, v75
	v_exp_f32_e32 v76, v76
	v_exp_f32_e32 v77, v77
	ds_read_b128 v[166:169], v202 offset:10240
	ds_read_b128 v[162:165], v202 offset:10752
	s_waitcnt lgkmcnt(12)
	v_mfma_f32_32x32x16_bf16 v[2:17], v[130:133], v[102:105], v[2:17]
	v_exp_f32_e32 v78, v78
	v_exp_f32_e32 v79, v79
	v_exp_f32_e32 v80, v80
	v_exp_f32_e32 v81, v81
	ds_read_b128 v[158:161], v202 offset:12288
	ds_read_b128 v[154:157], v202 offset:12800
	s_waitcnt lgkmcnt(12)
	v_mfma_f32_32x32x16_bf16 v[18:33], v[122:125], v[106:109], v[18:33]
	v_exp_f32_e32 v50, v50
	v_exp_f32_e32 v51, v51
	v_exp_f32_e32 v52, v52
	v_exp_f32_e32 v53, v53
	ds_read_b128 v[150:153], v202 offset:14336
	ds_read_b128 v[146:149], v202 offset:14848
	s_waitcnt lgkmcnt(12)
	v_mfma_f32_32x32x16_bf16 v[2:17], v[122:125], v[82:85], v[2:17]
	v_exp_f32_e32 v54, v54
	v_exp_f32_e32 v55, v55
	v_exp_f32_e32 v56, v56
	v_exp_f32_e32 v57, v57
	s_waitcnt lgkmcnt(10)
	v_mfma_f32_32x32x16_bf16 v[18:33], v[114:117], v[86:89], v[18:33]
	v_exp_f32_e32 v58, v58
	v_exp_f32_e32 v59, v59
	v_exp_f32_e32 v60, v60
	v_exp_f32_e32 v61, v61
	s_waitcnt vmcnt(2) lgkmcnt(0)
	s_barrier
	s_waitcnt lgkmcnt(8)
	v_mfma_f32_32x32x16_bf16 v[2:17], v[114:117], v[90:93], v[2:17]
	v_exp_f32_e32 v62, v62
	v_exp_f32_e32 v63, v63
	v_exp_f32_e32 v64, v64
	v_exp_f32_e32 v65, v65
